# phase 0 without the cross-workgroup K split: each workgroup owns 64 modulation columns, sums its 32 K-block partials in LDS in the baseline order and finalises MODF in place; the finalize items and on
# speedup vs baseline: 1.0197x; 1.0086x over previous
.LBB0_8:
	s_cmpk_gt_i32 s2, 0xbf
	s_cbranch_scc1 .Lgv_end
	s_load_dwordx2 s[30:31], s[8:9], 0x28
	s_load_dwordx2 s[28:29], s[8:9], 0x30
	s_load_dwordx2 s[34:35], s[8:9], 0x40
	s_load_dwordx2 s[36:37], s[8:9], 0x48
	s_cmpk_gt_i32 s2, 0x5f
	s_cselect_b32 s14, 1, 0
	s_mul_i32 s15, s14, 0x60
	s_sub_i32 s15, s2, s15
	s_lshl_b32 s15, s15, 6
	v_lshlrev_b32_e32 v10, 2, v1
	s_waitcnt lgkmcnt(0)
	global_load_dword v16, v10, s[28:29]
	global_load_dword v17, v10, s[28:29] offset:2048
	global_load_dword v18, v10, s[30:31]
	global_load_dword v19, v10, s[30:31] offset:2048
	v_add_u32_e32 v11, 0x1000, v10
	global_load_dword v20, v11, s[30:31]
	v_add_u32_e32 v11, 0x1800, v10
	global_load_dword v21, v11, s[30:31]
	v_add_u32_e32 v11, 0x2000, v10
	global_load_dword v22, v11, s[30:31]
	v_add_u32_e32 v11, 0x2800, v10
	global_load_dword v23, v11, s[30:31]
	v_add_u32_e32 v11, 0x3000, v10
	global_load_dword v24, v11, s[30:31]
	v_add_u32_e32 v11, 0x3800, v10
	global_load_dword v25, v11, s[30:31]
	s_waitcnt vmcnt(9)
	v_mov_b32_e32 v2, v16
	v_mul_f32_e32 v4, 0xbfb8aa3b, v2
	v_rndne_f32_e32 v5, v4
	v_fma_f32 v6, v2, s3, -v4
	v_sub_f32_e32 v4, v4, v5
	v_fmac_f32_e32 v6, 0xb2a5705f, v2
	v_add_f32_e32 v4, v4, v6
	v_cvt_i32_f32_e32 v5, v5
	v_exp_f32_e32 v4, v4
	v_cmp_nlt_f32_e32 vcc, s18, v2
	v_ldexp_f32 v4, v4, v5
	s_nop 0
	v_cndmask_b32_e32 v4, 0, v4, vcc
	v_cmp_ngt_f32_e32 vcc, s19, v2
	s_nop 1
	v_cndmask_b32_e32 v4, v15, v4, vcc
	v_add_f32_e32 v4, 1.0, v4
	v_div_scale_f32 v5, s[22:23], v4, v4, v2
	v_rcp_f32_e32 v6, v5
	v_div_scale_f32 v7, vcc, v2, v4, v2
	v_fma_f32 v8, -v5, v6, 1.0
	v_fmac_f32_e32 v6, v8, v6
	v_mul_f32_e32 v8, v7, v6
	v_fma_f32 v9, -v5, v8, v7
	v_fmac_f32_e32 v8, v9, v6
	v_fma_f32 v5, -v5, v8, v7
	v_div_fmas_f32 v5, v5, v6, v8
	v_div_fixup_f32 v2, v5, v4, v2
	ds_write_b32 v10, v2
	s_waitcnt vmcnt(8)
	v_mov_b32_e32 v2, v17
	v_mul_f32_e32 v4, 0xbfb8aa3b, v2
	v_rndne_f32_e32 v5, v4
	v_fma_f32 v6, v2, s3, -v4
	v_sub_f32_e32 v4, v4, v5
	v_fmac_f32_e32 v6, 0xb2a5705f, v2
	v_add_f32_e32 v4, v4, v6
	v_cvt_i32_f32_e32 v5, v5
	v_exp_f32_e32 v4, v4
	v_cmp_nlt_f32_e32 vcc, s18, v2
	v_ldexp_f32 v4, v4, v5
	s_nop 0
	v_cndmask_b32_e32 v4, 0, v4, vcc
	v_cmp_ngt_f32_e32 vcc, s19, v2
	s_nop 1
	v_cndmask_b32_e32 v4, v15, v4, vcc
	v_add_f32_e32 v4, 1.0, v4
	v_div_scale_f32 v5, s[22:23], v4, v4, v2
	v_rcp_f32_e32 v6, v5
	v_div_scale_f32 v7, vcc, v2, v4, v2
	v_fma_f32 v8, -v5, v6, 1.0
	v_fmac_f32_e32 v6, v8, v6
	v_mul_f32_e32 v8, v7, v6
	v_fma_f32 v9, -v5, v8, v7
	v_fmac_f32_e32 v8, v9, v6
	v_fma_f32 v5, -v5, v8, v7
	v_div_fmas_f32 v5, v5, v6, v8
	v_div_fixup_f32 v2, v5, v4, v2
	ds_write_b32 v10, v2 offset:2048
	s_waitcnt vmcnt(7)
	v_mov_b32_e32 v2, v18
	v_mul_f32_e32 v4, 0xbfb8aa3b, v2
	v_rndne_f32_e32 v5, v4
	v_fma_f32 v6, v2, s3, -v4
	v_sub_f32_e32 v4, v4, v5
	v_fmac_f32_e32 v6, 0xb2a5705f, v2
	v_add_f32_e32 v4, v4, v6
	v_cvt_i32_f32_e32 v5, v5
	v_exp_f32_e32 v4, v4
	v_cmp_nlt_f32_e32 vcc, s18, v2
	v_ldexp_f32 v4, v4, v5
	s_nop 0
	v_cndmask_b32_e32 v4, 0, v4, vcc
	v_cmp_ngt_f32_e32 vcc, s19, v2
	s_nop 1
	v_cndmask_b32_e32 v4, v15, v4, vcc
	v_add_f32_e32 v4, 1.0, v4
	v_div_scale_f32 v5, s[22:23], v4, v4, v2
	v_rcp_f32_e32 v6, v5
	v_div_scale_f32 v7, vcc, v2, v4, v2
	v_fma_f32 v8, -v5, v6, 1.0
	v_fmac_f32_e32 v6, v8, v6
	v_mul_f32_e32 v8, v7, v6
	v_fma_f32 v9, -v5, v8, v7
	v_fmac_f32_e32 v8, v9, v6
	v_fma_f32 v5, -v5, v8, v7
	v_div_fmas_f32 v5, v5, v6, v8
	v_div_fixup_f32 v2, v5, v4, v2
	ds_write_b32 v10, v2 offset:4096
	s_waitcnt vmcnt(6)
	v_mov_b32_e32 v2, v19
	v_mul_f32_e32 v4, 0xbfb8aa3b, v2
	v_rndne_f32_e32 v5, v4
	v_fma_f32 v6, v2, s3, -v4
	v_sub_f32_e32 v4, v4, v5
	v_fmac_f32_e32 v6, 0xb2a5705f, v2
	v_add_f32_e32 v4, v4, v6
	v_cvt_i32_f32_e32 v5, v5
	v_exp_f32_e32 v4, v4
	v_cmp_nlt_f32_e32 vcc, s18, v2
	v_ldexp_f32 v4, v4, v5
	s_nop 0
	v_cndmask_b32_e32 v4, 0, v4, vcc
	v_cmp_ngt_f32_e32 vcc, s19, v2
	s_nop 1
	v_cndmask_b32_e32 v4, v15, v4, vcc
	v_add_f32_e32 v4, 1.0, v4
	v_div_scale_f32 v5, s[22:23], v4, v4, v2
	v_rcp_f32_e32 v6, v5
	v_div_scale_f32 v7, vcc, v2, v4, v2
	v_fma_f32 v8, -v5, v6, 1.0
	v_fmac_f32_e32 v6, v8, v6
	v_mul_f32_e32 v8, v7, v6
	v_fma_f32 v9, -v5, v8, v7
	v_fmac_f32_e32 v8, v9, v6
	v_fma_f32 v5, -v5, v8, v7
	v_div_fmas_f32 v5, v5, v6, v8
	v_div_fixup_f32 v2, v5, v4, v2
	ds_write_b32 v10, v2 offset:6144
	s_waitcnt vmcnt(5)
	v_mov_b32_e32 v2, v20
	v_mul_f32_e32 v4, 0xbfb8aa3b, v2
	v_rndne_f32_e32 v5, v4
	v_fma_f32 v6, v2, s3, -v4
	v_sub_f32_e32 v4, v4, v5
	v_fmac_f32_e32 v6, 0xb2a5705f, v2
	v_add_f32_e32 v4, v4, v6
	v_cvt_i32_f32_e32 v5, v5
	v_exp_f32_e32 v4, v4
	v_cmp_nlt_f32_e32 vcc, s18, v2
	v_ldexp_f32 v4, v4, v5
	s_nop 0
	v_cndmask_b32_e32 v4, 0, v4, vcc
	v_cmp_ngt_f32_e32 vcc, s19, v2
	s_nop 1
	v_cndmask_b32_e32 v4, v15, v4, vcc
	v_add_f32_e32 v4, 1.0, v4
	v_div_scale_f32 v5, s[22:23], v4, v4, v2
	v_rcp_f32_e32 v6, v5
	v_div_scale_f32 v7, vcc, v2, v4, v2
	v_fma_f32 v8, -v5, v6, 1.0
	v_fmac_f32_e32 v6, v8, v6
	v_mul_f32_e32 v8, v7, v6
	v_fma_f32 v9, -v5, v8, v7
	v_fmac_f32_e32 v8, v9, v6
	v_fma_f32 v5, -v5, v8, v7
	v_div_fmas_f32 v5, v5, v6, v8
	v_div_fixup_f32 v2, v5, v4, v2
	ds_write_b32 v10, v2 offset:8192
	s_waitcnt vmcnt(4)
	v_mov_b32_e32 v2, v21
	v_mul_f32_e32 v4, 0xbfb8aa3b, v2
	v_rndne_f32_e32 v5, v4
	v_fma_f32 v6, v2, s3, -v4
	v_sub_f32_e32 v4, v4, v5
	v_fmac_f32_e32 v6, 0xb2a5705f, v2
	v_add_f32_e32 v4, v4, v6
	v_cvt_i32_f32_e32 v5, v5
	v_exp_f32_e32 v4, v4
	v_cmp_nlt_f32_e32 vcc, s18, v2
	v_ldexp_f32 v4, v4, v5
	s_nop 0
	v_cndmask_b32_e32 v4, 0, v4, vcc
	v_cmp_ngt_f32_e32 vcc, s19, v2
	s_nop 1
	v_cndmask_b32_e32 v4, v15, v4, vcc
	v_add_f32_e32 v4, 1.0, v4
	v_div_scale_f32 v5, s[22:23], v4, v4, v2
	v_rcp_f32_e32 v6, v5
	v_div_scale_f32 v7, vcc, v2, v4, v2
	v_fma_f32 v8, -v5, v6, 1.0
	v_fmac_f32_e32 v6, v8, v6
	v_mul_f32_e32 v8, v7, v6
	v_fma_f32 v9, -v5, v8, v7
	v_fmac_f32_e32 v8, v9, v6
	v_fma_f32 v5, -v5, v8, v7
	v_div_fmas_f32 v5, v5, v6, v8
	v_div_fixup_f32 v2, v5, v4, v2
	ds_write_b32 v10, v2 offset:10240
	s_waitcnt vmcnt(3)
	v_mov_b32_e32 v2, v22
	v_mul_f32_e32 v4, 0xbfb8aa3b, v2
	v_rndne_f32_e32 v5, v4
	v_fma_f32 v6, v2, s3, -v4
	v_sub_f32_e32 v4, v4, v5
	v_fmac_f32_e32 v6, 0xb2a5705f, v2
	v_add_f32_e32 v4, v4, v6
	v_cvt_i32_f32_e32 v5, v5
	v_exp_f32_e32 v4, v4
	v_cmp_nlt_f32_e32 vcc, s18, v2
	v_ldexp_f32 v4, v4, v5
	s_nop 0
	v_cndmask_b32_e32 v4, 0, v4, vcc
	v_cmp_ngt_f32_e32 vcc, s19, v2
	s_nop 1
	v_cndmask_b32_e32 v4, v15, v4, vcc
	v_add_f32_e32 v4, 1.0, v4
	v_div_scale_f32 v5, s[22:23], v4, v4, v2
	v_rcp_f32_e32 v6, v5
	v_div_scale_f32 v7, vcc, v2, v4, v2
	v_fma_f32 v8, -v5, v6, 1.0
	v_fmac_f32_e32 v6, v8, v6
	v_mul_f32_e32 v8, v7, v6
	v_fma_f32 v9, -v5, v8, v7
	v_fmac_f32_e32 v8, v9, v6
	v_fma_f32 v5, -v5, v8, v7
	v_div_fmas_f32 v5, v5, v6, v8
	v_div_fixup_f32 v2, v5, v4, v2
	ds_write_b32 v10, v2 offset:12288
	s_waitcnt vmcnt(2)
	v_mov_b32_e32 v2, v23
	v_mul_f32_e32 v4, 0xbfb8aa3b, v2
	v_rndne_f32_e32 v5, v4
	v_fma_f32 v6, v2, s3, -v4
	v_sub_f32_e32 v4, v4, v5
	v_fmac_f32_e32 v6, 0xb2a5705f, v2
	v_add_f32_e32 v4, v4, v6
	v_cvt_i32_f32_e32 v5, v5
	v_exp_f32_e32 v4, v4
	v_cmp_nlt_f32_e32 vcc, s18, v2
	v_ldexp_f32 v4, v4, v5
	s_nop 0
	v_cndmask_b32_e32 v4, 0, v4, vcc
	v_cmp_ngt_f32_e32 vcc, s19, v2
	s_nop 1
	v_cndmask_b32_e32 v4, v15, v4, vcc
	v_add_f32_e32 v4, 1.0, v4
	v_div_scale_f32 v5, s[22:23], v4, v4, v2
	v_rcp_f32_e32 v6, v5
	v_div_scale_f32 v7, vcc, v2, v4, v2
	v_fma_f32 v8, -v5, v6, 1.0
	v_fmac_f32_e32 v6, v8, v6
	v_mul_f32_e32 v8, v7, v6
	v_fma_f32 v9, -v5, v8, v7
	v_fmac_f32_e32 v8, v9, v6
	v_fma_f32 v5, -v5, v8, v7
	v_div_fmas_f32 v5, v5, v6, v8
	v_div_fixup_f32 v2, v5, v4, v2
	ds_write_b32 v10, v2 offset:14336
	s_waitcnt vmcnt(1)
	v_mov_b32_e32 v2, v24
	v_mul_f32_e32 v4, 0xbfb8aa3b, v2
	v_rndne_f32_e32 v5, v4
	v_fma_f32 v6, v2, s3, -v4
	v_sub_f32_e32 v4, v4, v5
	v_fmac_f32_e32 v6, 0xb2a5705f, v2
	v_add_f32_e32 v4, v4, v6
	v_cvt_i32_f32_e32 v5, v5
	v_exp_f32_e32 v4, v4
	v_cmp_nlt_f32_e32 vcc, s18, v2
	v_ldexp_f32 v4, v4, v5
	s_nop 0
	v_cndmask_b32_e32 v4, 0, v4, vcc
	v_cmp_ngt_f32_e32 vcc, s19, v2
	s_nop 1
	v_cndmask_b32_e32 v4, v15, v4, vcc
	v_add_f32_e32 v4, 1.0, v4
	v_div_scale_f32 v5, s[22:23], v4, v4, v2
	v_rcp_f32_e32 v6, v5
	v_div_scale_f32 v7, vcc, v2, v4, v2
	v_fma_f32 v8, -v5, v6, 1.0
	v_fmac_f32_e32 v6, v8, v6
	v_mul_f32_e32 v8, v7, v6
	v_fma_f32 v9, -v5, v8, v7
	v_fmac_f32_e32 v8, v9, v6
	v_fma_f32 v5, -v5, v8, v7
	v_div_fmas_f32 v5, v5, v6, v8
	v_div_fixup_f32 v2, v5, v4, v2
	ds_write_b32 v10, v2 offset:16384
	s_waitcnt vmcnt(0)
	v_mov_b32_e32 v2, v25
	v_mul_f32_e32 v4, 0xbfb8aa3b, v2
	v_rndne_f32_e32 v5, v4
	v_fma_f32 v6, v2, s3, -v4
	v_sub_f32_e32 v4, v4, v5
	v_fmac_f32_e32 v6, 0xb2a5705f, v2
	v_add_f32_e32 v4, v4, v6
	v_cvt_i32_f32_e32 v5, v5
	v_exp_f32_e32 v4, v4
	v_cmp_nlt_f32_e32 vcc, s18, v2
	v_ldexp_f32 v4, v4, v5
	s_nop 0
	v_cndmask_b32_e32 v4, 0, v4, vcc
	v_cmp_ngt_f32_e32 vcc, s19, v2
	s_nop 1
	v_cndmask_b32_e32 v4, v15, v4, vcc
	v_add_f32_e32 v4, 1.0, v4
	v_div_scale_f32 v5, s[22:23], v4, v4, v2
	v_rcp_f32_e32 v6, v5
	v_div_scale_f32 v7, vcc, v2, v4, v2
	v_fma_f32 v8, -v5, v6, 1.0
	v_fmac_f32_e32 v6, v8, v6
	v_mul_f32_e32 v8, v7, v6
	v_fma_f32 v9, -v5, v8, v7
	v_fmac_f32_e32 v8, v9, v6
	v_fma_f32 v5, -v5, v8, v7
	v_div_fmas_f32 v5, v5, v6, v8
	v_div_fixup_f32 v2, v5, v4, v2
	ds_write_b32 v10, v2 offset:18432
	s_waitcnt lgkmcnt(0)
	s_barrier
	v_readfirstlane_b32 s16, v1
	s_lshr_b32 s16, s16, 6
	v_and_b32_e32 v11, 63, v1
	v_and_b32_e32 v12, 15, v11
	v_lshrrev_b32_e32 v13, 4, v11
	v_lshlrev_b32_e32 v14, 4, v12
	s_lshl_b32 s17, s15, 2
	v_add_u32_e32 v14, s17, v14
	v_mul_u32_u24_e32 v11, 0xc0000, v13
	v_add_u32_e32 v14, v11, v14
	s_mul_i32 s20, s14, 0x1800000
	s_mul_i32 s21, s16, 0x300000
	s_add_u32 s20, s20, s21
	s_add_u32 s20, s12, s20
	s_addc_u32 s21, s13, 0
	v_lshl_add_u32 v11, s16, 2, v13
	v_lshlrev_b32_e32 v11, 7, v11
	v_mov_b32_e32 v100, 0
	v_mov_b32_e32 v101, 0
	v_mov_b32_e32 v102, 0
	v_mov_b32_e32 v103, 0
	v_mov_b32_e32 v104, 0
	v_mov_b32_e32 v105, 0
	v_mov_b32_e32 v106, 0
	v_mov_b32_e32 v107, 0
	v_mov_b32_e32 v108, 0
	v_mov_b32_e32 v109, 0
	v_mov_b32_e32 v110, 0
	v_mov_b32_e32 v111, 0
	v_mov_b32_e32 v112, 0
	v_mov_b32_e32 v113, 0
	v_mov_b32_e32 v114, 0
	v_mov_b32_e32 v115, 0
	v_mov_b32_e32 v116, 0
	v_mov_b32_e32 v117, 0
	v_mov_b32_e32 v118, 0
	v_mov_b32_e32 v119, 0
	global_load_dwordx4 v[16:19], v14, s[20:21] nt
	s_add_u32 s20, s20, 0x6000
	s_addc_u32 s21, s21, 0
	global_load_dwordx4 v[20:23], v14, s[20:21] nt
	s_add_u32 s20, s20, 0x6000
	s_addc_u32 s21, s21, 0
	global_load_dwordx4 v[24:27], v14, s[20:21] nt
	s_add_u32 s20, s20, 0x6000
	s_addc_u32 s21, s21, 0
	global_load_dwordx4 v[28:31], v14, s[20:21] nt
	s_add_u32 s20, s20, 0x6000
	s_addc_u32 s21, s21, 0
	global_load_dwordx4 v[32:35], v14, s[20:21] nt
	s_add_u32 s20, s20, 0x6000
	s_addc_u32 s21, s21, 0
	global_load_dwordx4 v[36:39], v14, s[20:21] nt
	s_add_u32 s20, s20, 0x6000
	s_addc_u32 s21, s21, 0
	global_load_dwordx4 v[40:43], v14, s[20:21] nt
	s_add_u32 s20, s20, 0x6000
	s_addc_u32 s21, s21, 0
	global_load_dwordx4 v[44:47], v14, s[20:21] nt
	s_add_u32 s20, s20, 0x6000
	s_addc_u32 s21, s21, 0
	global_load_dwordx4 v[48:51], v14, s[20:21] nt
	s_add_u32 s20, s20, 0x6000
	s_addc_u32 s21, s21, 0
	global_load_dwordx4 v[52:55], v14, s[20:21] nt
	s_add_u32 s20, s20, 0x6000
	s_addc_u32 s21, s21, 0
	global_load_dwordx4 v[56:59], v14, s[20:21] nt
	s_add_u32 s20, s20, 0x6000
	s_addc_u32 s21, s21, 0
	global_load_dwordx4 v[60:63], v14, s[20:21] nt
	s_add_u32 s20, s20, 0x6000
	s_addc_u32 s21, s21, 0
	global_load_dwordx4 v[64:67], v14, s[20:21] nt
	s_add_u32 s20, s20, 0x6000
	s_addc_u32 s21, s21, 0
	global_load_dwordx4 v[68:71], v14, s[20:21] nt
	s_add_u32 s20, s20, 0x6000
	s_addc_u32 s21, s21, 0
	global_load_dwordx4 v[72:75], v14, s[20:21] nt
	s_add_u32 s20, s20, 0x6000
	s_addc_u32 s21, s21, 0
	global_load_dwordx4 v[76:79], v14, s[20:21] nt
	s_add_u32 s20, s20, 0x6000
	s_addc_u32 s21, s21, 0
	ds_read_b128 v[80:83], v11 offset:0
	ds_read_b128 v[84:87], v11 offset:16
	ds_read_b128 v[88:91], v11 offset:32
	ds_read_b128 v[92:95], v11 offset:48
	ds_read_b128 v[120:123], v11 offset:4096
	ds_read_b128 v[124:127], v11 offset:4112
	ds_read_b128 v[128:131], v11 offset:4128
	ds_read_b128 v[132:135], v11 offset:4144
	ds_read_b128 v[136:139], v11 offset:8192
	ds_read_b128 v[140:143], v11 offset:8208
	ds_read_b128 v[144:147], v11 offset:8224
	ds_read_b128 v[148:151], v11 offset:8240
	ds_read_b128 v[152:155], v11 offset:12288
	ds_read_b128 v[156:159], v11 offset:12304
	ds_read_b128 v[160:163], v11 offset:12320
	ds_read_b128 v[164:167], v11 offset:12336
	ds_read_b128 v[180:183], v11 offset:16384
	ds_read_b128 v[184:187], v11 offset:16400
	ds_read_b128 v[188:191], v11 offset:16416
	ds_read_b128 v[192:195], v11 offset:16432
	s_waitcnt lgkmcnt(0)
	s_waitcnt vmcnt(15)
	v_fmac_f32_e32 v100, v16, v80
	v_fmac_f32_e32 v101, v17, v80
	v_fmac_f32_e32 v102, v18, v80
	v_fmac_f32_e32 v103, v19, v80
	v_fmac_f32_e32 v104, v16, v120
	v_fmac_f32_e32 v105, v17, v120
	v_fmac_f32_e32 v106, v18, v120
	v_fmac_f32_e32 v107, v19, v120
	v_fmac_f32_e32 v108, v16, v136
	v_fmac_f32_e32 v109, v17, v136
	v_fmac_f32_e32 v110, v18, v136
	v_fmac_f32_e32 v111, v19, v136
	v_fmac_f32_e32 v112, v16, v152
	v_fmac_f32_e32 v113, v17, v152
	v_fmac_f32_e32 v114, v18, v152
	v_fmac_f32_e32 v115, v19, v152
	v_fmac_f32_e32 v116, v16, v180
	v_fmac_f32_e32 v117, v17, v180
	v_fmac_f32_e32 v118, v18, v180
	v_fmac_f32_e32 v119, v19, v180
	s_waitcnt vmcnt(14)
	v_fmac_f32_e32 v100, v20, v81
	v_fmac_f32_e32 v101, v21, v81
	v_fmac_f32_e32 v102, v22, v81
	v_fmac_f32_e32 v103, v23, v81
	v_fmac_f32_e32 v104, v20, v121
	v_fmac_f32_e32 v105, v21, v121
	v_fmac_f32_e32 v106, v22, v121
	v_fmac_f32_e32 v107, v23, v121
	v_fmac_f32_e32 v108, v20, v137
	v_fmac_f32_e32 v109, v21, v137
	v_fmac_f32_e32 v110, v22, v137
	v_fmac_f32_e32 v111, v23, v137
	v_fmac_f32_e32 v112, v20, v153
	v_fmac_f32_e32 v113, v21, v153
	v_fmac_f32_e32 v114, v22, v153
	v_fmac_f32_e32 v115, v23, v153
	v_fmac_f32_e32 v116, v20, v181
	v_fmac_f32_e32 v117, v21, v181
	v_fmac_f32_e32 v118, v22, v181
	v_fmac_f32_e32 v119, v23, v181
	s_waitcnt vmcnt(13)
	v_fmac_f32_e32 v100, v24, v82
	v_fmac_f32_e32 v101, v25, v82
	v_fmac_f32_e32 v102, v26, v82
	v_fmac_f32_e32 v103, v27, v82
	v_fmac_f32_e32 v104, v24, v122
	v_fmac_f32_e32 v105, v25, v122
	v_fmac_f32_e32 v106, v26, v122
	v_fmac_f32_e32 v107, v27, v122
	v_fmac_f32_e32 v108, v24, v138
	v_fmac_f32_e32 v109, v25, v138
	v_fmac_f32_e32 v110, v26, v138
	v_fmac_f32_e32 v111, v27, v138
	v_fmac_f32_e32 v112, v24, v154
	v_fmac_f32_e32 v113, v25, v154
	v_fmac_f32_e32 v114, v26, v154
	v_fmac_f32_e32 v115, v27, v154
	v_fmac_f32_e32 v116, v24, v182
	v_fmac_f32_e32 v117, v25, v182
	v_fmac_f32_e32 v118, v26, v182
	v_fmac_f32_e32 v119, v27, v182
	s_waitcnt vmcnt(12)
	v_fmac_f32_e32 v100, v28, v83
	v_fmac_f32_e32 v101, v29, v83
	v_fmac_f32_e32 v102, v30, v83
	v_fmac_f32_e32 v103, v31, v83
	v_fmac_f32_e32 v104, v28, v123
	v_fmac_f32_e32 v105, v29, v123
	v_fmac_f32_e32 v106, v30, v123
	v_fmac_f32_e32 v107, v31, v123
	v_fmac_f32_e32 v108, v28, v139
	v_fmac_f32_e32 v109, v29, v139
	v_fmac_f32_e32 v110, v30, v139
	v_fmac_f32_e32 v111, v31, v139
	v_fmac_f32_e32 v112, v28, v155
	v_fmac_f32_e32 v113, v29, v155
	v_fmac_f32_e32 v114, v30, v155
	v_fmac_f32_e32 v115, v31, v155
	v_fmac_f32_e32 v116, v28, v183
	v_fmac_f32_e32 v117, v29, v183
	v_fmac_f32_e32 v118, v30, v183
	v_fmac_f32_e32 v119, v31, v183
	s_waitcnt vmcnt(11)
	v_fmac_f32_e32 v100, v32, v84
	v_fmac_f32_e32 v101, v33, v84
	v_fmac_f32_e32 v102, v34, v84
	v_fmac_f32_e32 v103, v35, v84
	v_fmac_f32_e32 v104, v32, v124
	v_fmac_f32_e32 v105, v33, v124
	v_fmac_f32_e32 v106, v34, v124
	v_fmac_f32_e32 v107, v35, v124
	v_fmac_f32_e32 v108, v32, v140
	v_fmac_f32_e32 v109, v33, v140
	v_fmac_f32_e32 v110, v34, v140
	v_fmac_f32_e32 v111, v35, v140
	v_fmac_f32_e32 v112, v32, v156
	v_fmac_f32_e32 v113, v33, v156
	v_fmac_f32_e32 v114, v34, v156
	v_fmac_f32_e32 v115, v35, v156
	v_fmac_f32_e32 v116, v32, v184
	v_fmac_f32_e32 v117, v33, v184
	v_fmac_f32_e32 v118, v34, v184
	v_fmac_f32_e32 v119, v35, v184
	s_waitcnt vmcnt(10)
	v_fmac_f32_e32 v100, v36, v85
	v_fmac_f32_e32 v101, v37, v85
	v_fmac_f32_e32 v102, v38, v85
	v_fmac_f32_e32 v103, v39, v85
	v_fmac_f32_e32 v104, v36, v125
	v_fmac_f32_e32 v105, v37, v125
	v_fmac_f32_e32 v106, v38, v125
	v_fmac_f32_e32 v107, v39, v125
	v_fmac_f32_e32 v108, v36, v141
	v_fmac_f32_e32 v109, v37, v141
	v_fmac_f32_e32 v110, v38, v141
	v_fmac_f32_e32 v111, v39, v141
	v_fmac_f32_e32 v112, v36, v157
	v_fmac_f32_e32 v113, v37, v157
	v_fmac_f32_e32 v114, v38, v157
	v_fmac_f32_e32 v115, v39, v157
	v_fmac_f32_e32 v116, v36, v185
	v_fmac_f32_e32 v117, v37, v185
	v_fmac_f32_e32 v118, v38, v185
	v_fmac_f32_e32 v119, v39, v185
	s_waitcnt vmcnt(9)
	v_fmac_f32_e32 v100, v40, v86
	v_fmac_f32_e32 v101, v41, v86
	v_fmac_f32_e32 v102, v42, v86
	v_fmac_f32_e32 v103, v43, v86
	v_fmac_f32_e32 v104, v40, v126
	v_fmac_f32_e32 v105, v41, v126
	v_fmac_f32_e32 v106, v42, v126
	v_fmac_f32_e32 v107, v43, v126
	v_fmac_f32_e32 v108, v40, v142
	v_fmac_f32_e32 v109, v41, v142
	v_fmac_f32_e32 v110, v42, v142
	v_fmac_f32_e32 v111, v43, v142
	v_fmac_f32_e32 v112, v40, v158
	v_fmac_f32_e32 v113, v41, v158
	v_fmac_f32_e32 v114, v42, v158
	v_fmac_f32_e32 v115, v43, v158
	v_fmac_f32_e32 v116, v40, v186
	v_fmac_f32_e32 v117, v41, v186
	v_fmac_f32_e32 v118, v42, v186
	v_fmac_f32_e32 v119, v43, v186
	s_waitcnt vmcnt(8)
	v_fmac_f32_e32 v100, v44, v87
	v_fmac_f32_e32 v101, v45, v87
	v_fmac_f32_e32 v102, v46, v87
	v_fmac_f32_e32 v103, v47, v87
	v_fmac_f32_e32 v104, v44, v127
	v_fmac_f32_e32 v105, v45, v127
	v_fmac_f32_e32 v106, v46, v127
	v_fmac_f32_e32 v107, v47, v127
	v_fmac_f32_e32 v108, v44, v143
	v_fmac_f32_e32 v109, v45, v143
	v_fmac_f32_e32 v110, v46, v143
	v_fmac_f32_e32 v111, v47, v143
	v_fmac_f32_e32 v112, v44, v159
	v_fmac_f32_e32 v113, v45, v159
	v_fmac_f32_e32 v114, v46, v159
	v_fmac_f32_e32 v115, v47, v159
	v_fmac_f32_e32 v116, v44, v187
	v_fmac_f32_e32 v117, v45, v187
	v_fmac_f32_e32 v118, v46, v187
	v_fmac_f32_e32 v119, v47, v187
	s_waitcnt vmcnt(7)
	v_fmac_f32_e32 v100, v48, v88
	v_fmac_f32_e32 v101, v49, v88
	v_fmac_f32_e32 v102, v50, v88
	v_fmac_f32_e32 v103, v51, v88
	v_fmac_f32_e32 v104, v48, v128
	v_fmac_f32_e32 v105, v49, v128
	v_fmac_f32_e32 v106, v50, v128
	v_fmac_f32_e32 v107, v51, v128
	v_fmac_f32_e32 v108, v48, v144
	v_fmac_f32_e32 v109, v49, v144
	v_fmac_f32_e32 v110, v50, v144
	v_fmac_f32_e32 v111, v51, v144
	v_fmac_f32_e32 v112, v48, v160
	v_fmac_f32_e32 v113, v49, v160
	v_fmac_f32_e32 v114, v50, v160
	v_fmac_f32_e32 v115, v51, v160
	v_fmac_f32_e32 v116, v48, v188
	v_fmac_f32_e32 v117, v49, v188
	v_fmac_f32_e32 v118, v50, v188
	v_fmac_f32_e32 v119, v51, v188
	s_waitcnt vmcnt(6)
	v_fmac_f32_e32 v100, v52, v89
	v_fmac_f32_e32 v101, v53, v89
	v_fmac_f32_e32 v102, v54, v89
	v_fmac_f32_e32 v103, v55, v89
	v_fmac_f32_e32 v104, v52, v129
	v_fmac_f32_e32 v105, v53, v129
	v_fmac_f32_e32 v106, v54, v129
	v_fmac_f32_e32 v107, v55, v129
	v_fmac_f32_e32 v108, v52, v145
	v_fmac_f32_e32 v109, v53, v145
	v_fmac_f32_e32 v110, v54, v145
	v_fmac_f32_e32 v111, v55, v145
	v_fmac_f32_e32 v112, v52, v161
	v_fmac_f32_e32 v113, v53, v161
	v_fmac_f32_e32 v114, v54, v161
	v_fmac_f32_e32 v115, v55, v161
	v_fmac_f32_e32 v116, v52, v189
	v_fmac_f32_e32 v117, v53, v189
	v_fmac_f32_e32 v118, v54, v189
	v_fmac_f32_e32 v119, v55, v189
	s_waitcnt vmcnt(5)
	v_fmac_f32_e32 v100, v56, v90
	v_fmac_f32_e32 v101, v57, v90
	v_fmac_f32_e32 v102, v58, v90
	v_fmac_f32_e32 v103, v59, v90
	v_fmac_f32_e32 v104, v56, v130
	v_fmac_f32_e32 v105, v57, v130
	v_fmac_f32_e32 v106, v58, v130
	v_fmac_f32_e32 v107, v59, v130
	v_fmac_f32_e32 v108, v56, v146
	v_fmac_f32_e32 v109, v57, v146
	v_fmac_f32_e32 v110, v58, v146
	v_fmac_f32_e32 v111, v59, v146
	v_fmac_f32_e32 v112, v56, v162
	v_fmac_f32_e32 v113, v57, v162
	v_fmac_f32_e32 v114, v58, v162
	v_fmac_f32_e32 v115, v59, v162
	v_fmac_f32_e32 v116, v56, v190
	v_fmac_f32_e32 v117, v57, v190
	v_fmac_f32_e32 v118, v58, v190
	v_fmac_f32_e32 v119, v59, v190
	s_waitcnt vmcnt(4)
	v_fmac_f32_e32 v100, v60, v91
	v_fmac_f32_e32 v101, v61, v91
	v_fmac_f32_e32 v102, v62, v91
	v_fmac_f32_e32 v103, v63, v91
	v_fmac_f32_e32 v104, v60, v131
	v_fmac_f32_e32 v105, v61, v131
	v_fmac_f32_e32 v106, v62, v131
	v_fmac_f32_e32 v107, v63, v131
	v_fmac_f32_e32 v108, v60, v147
	v_fmac_f32_e32 v109, v61, v147
	v_fmac_f32_e32 v110, v62, v147
	v_fmac_f32_e32 v111, v63, v147
	v_fmac_f32_e32 v112, v60, v163
	v_fmac_f32_e32 v113, v61, v163
	v_fmac_f32_e32 v114, v62, v163
	v_fmac_f32_e32 v115, v63, v163
	v_fmac_f32_e32 v116, v60, v191
	v_fmac_f32_e32 v117, v61, v191
	v_fmac_f32_e32 v118, v62, v191
	v_fmac_f32_e32 v119, v63, v191
	s_waitcnt vmcnt(3)
	v_fmac_f32_e32 v100, v64, v92
	v_fmac_f32_e32 v101, v65, v92
	v_fmac_f32_e32 v102, v66, v92
	v_fmac_f32_e32 v103, v67, v92
	v_fmac_f32_e32 v104, v64, v132
	v_fmac_f32_e32 v105, v65, v132
	v_fmac_f32_e32 v106, v66, v132
	v_fmac_f32_e32 v107, v67, v132
	v_fmac_f32_e32 v108, v64, v148
	v_fmac_f32_e32 v109, v65, v148
	v_fmac_f32_e32 v110, v66, v148
	v_fmac_f32_e32 v111, v67, v148
	v_fmac_f32_e32 v112, v64, v164
	v_fmac_f32_e32 v113, v65, v164
	v_fmac_f32_e32 v114, v66, v164
	v_fmac_f32_e32 v115, v67, v164
	v_fmac_f32_e32 v116, v64, v192
	v_fmac_f32_e32 v117, v65, v192
	v_fmac_f32_e32 v118, v66, v192
	v_fmac_f32_e32 v119, v67, v192
	s_waitcnt vmcnt(2)
	v_fmac_f32_e32 v100, v68, v93
	v_fmac_f32_e32 v101, v69, v93
	v_fmac_f32_e32 v102, v70, v93
	v_fmac_f32_e32 v103, v71, v93
	v_fmac_f32_e32 v104, v68, v133
	v_fmac_f32_e32 v105, v69, v133
	v_fmac_f32_e32 v106, v70, v133
	v_fmac_f32_e32 v107, v71, v133
	v_fmac_f32_e32 v108, v68, v149
	v_fmac_f32_e32 v109, v69, v149
	v_fmac_f32_e32 v110, v70, v149
	v_fmac_f32_e32 v111, v71, v149
	v_fmac_f32_e32 v112, v68, v165
	v_fmac_f32_e32 v113, v69, v165
	v_fmac_f32_e32 v114, v70, v165
	v_fmac_f32_e32 v115, v71, v165
	v_fmac_f32_e32 v116, v68, v193
	v_fmac_f32_e32 v117, v69, v193
	v_fmac_f32_e32 v118, v70, v193
	v_fmac_f32_e32 v119, v71, v193
	s_waitcnt vmcnt(1)
	v_fmac_f32_e32 v100, v72, v94
	v_fmac_f32_e32 v101, v73, v94
	v_fmac_f32_e32 v102, v74, v94
	v_fmac_f32_e32 v103, v75, v94
	v_fmac_f32_e32 v104, v72, v134
	v_fmac_f32_e32 v105, v73, v134
	v_fmac_f32_e32 v106, v74, v134
	v_fmac_f32_e32 v107, v75, v134
	v_fmac_f32_e32 v108, v72, v150
	v_fmac_f32_e32 v109, v73, v150
	v_fmac_f32_e32 v110, v74, v150
	v_fmac_f32_e32 v111, v75, v150
	v_fmac_f32_e32 v112, v72, v166
	v_fmac_f32_e32 v113, v73, v166
	v_fmac_f32_e32 v114, v74, v166
	v_fmac_f32_e32 v115, v75, v166
	v_fmac_f32_e32 v116, v72, v194
	v_fmac_f32_e32 v117, v73, v194
	v_fmac_f32_e32 v118, v74, v194
	v_fmac_f32_e32 v119, v75, v194
	s_waitcnt vmcnt(0)
	v_fmac_f32_e32 v100, v76, v95
	v_fmac_f32_e32 v101, v77, v95
	v_fmac_f32_e32 v102, v78, v95
	v_fmac_f32_e32 v103, v79, v95
	v_fmac_f32_e32 v104, v76, v135
	v_fmac_f32_e32 v105, v77, v135
	v_fmac_f32_e32 v106, v78, v135
	v_fmac_f32_e32 v107, v79, v135
	v_fmac_f32_e32 v108, v76, v151
	v_fmac_f32_e32 v109, v77, v151
	v_fmac_f32_e32 v110, v78, v151
	v_fmac_f32_e32 v111, v79, v151
	v_fmac_f32_e32 v112, v76, v167
	v_fmac_f32_e32 v113, v77, v167
	v_fmac_f32_e32 v114, v78, v167
	v_fmac_f32_e32 v115, v79, v167
	v_fmac_f32_e32 v116, v76, v195
	v_fmac_f32_e32 v117, v77, v195
	v_fmac_f32_e32 v118, v78, v195
	v_fmac_f32_e32 v119, v79, v195
	global_load_dwordx4 v[16:19], v14, s[20:21] nt
	s_add_u32 s20, s20, 0x6000
	s_addc_u32 s21, s21, 0
	global_load_dwordx4 v[20:23], v14, s[20:21] nt
	s_add_u32 s20, s20, 0x6000
	s_addc_u32 s21, s21, 0
	global_load_dwordx4 v[24:27], v14, s[20:21] nt
	s_add_u32 s20, s20, 0x6000
	s_addc_u32 s21, s21, 0
	global_load_dwordx4 v[28:31], v14, s[20:21] nt
	s_add_u32 s20, s20, 0x6000
	s_addc_u32 s21, s21, 0
	global_load_dwordx4 v[32:35], v14, s[20:21] nt
	s_add_u32 s20, s20, 0x6000
	s_addc_u32 s21, s21, 0
	global_load_dwordx4 v[36:39], v14, s[20:21] nt
	s_add_u32 s20, s20, 0x6000
	s_addc_u32 s21, s21, 0
	global_load_dwordx4 v[40:43], v14, s[20:21] nt
	s_add_u32 s20, s20, 0x6000
	s_addc_u32 s21, s21, 0
	global_load_dwordx4 v[44:47], v14, s[20:21] nt
	s_add_u32 s20, s20, 0x6000
	s_addc_u32 s21, s21, 0
	global_load_dwordx4 v[48:51], v14, s[20:21] nt
	s_add_u32 s20, s20, 0x6000
	s_addc_u32 s21, s21, 0
	global_load_dwordx4 v[52:55], v14, s[20:21] nt
	s_add_u32 s20, s20, 0x6000
	s_addc_u32 s21, s21, 0
	global_load_dwordx4 v[56:59], v14, s[20:21] nt
	s_add_u32 s20, s20, 0x6000
	s_addc_u32 s21, s21, 0
	global_load_dwordx4 v[60:63], v14, s[20:21] nt
	s_add_u32 s20, s20, 0x6000
	s_addc_u32 s21, s21, 0
	global_load_dwordx4 v[64:67], v14, s[20:21] nt
	s_add_u32 s20, s20, 0x6000
	s_addc_u32 s21, s21, 0
	global_load_dwordx4 v[68:71], v14, s[20:21] nt
	s_add_u32 s20, s20, 0x6000
	s_addc_u32 s21, s21, 0
	global_load_dwordx4 v[72:75], v14, s[20:21] nt
	s_add_u32 s20, s20, 0x6000
	s_addc_u32 s21, s21, 0
	global_load_dwordx4 v[76:79], v14, s[20:21] nt
	s_add_u32 s20, s20, 0x6000
	s_addc_u32 s21, s21, 0
	ds_read_b128 v[80:83], v11 offset:64
	ds_read_b128 v[84:87], v11 offset:80
	ds_read_b128 v[88:91], v11 offset:96
	ds_read_b128 v[92:95], v11 offset:112
	ds_read_b128 v[120:123], v11 offset:4160
	ds_read_b128 v[124:127], v11 offset:4176
	ds_read_b128 v[128:131], v11 offset:4192
	ds_read_b128 v[132:135], v11 offset:4208
	ds_read_b128 v[136:139], v11 offset:8256
	ds_read_b128 v[140:143], v11 offset:8272
	ds_read_b128 v[144:147], v11 offset:8288
	ds_read_b128 v[148:151], v11 offset:8304
	ds_read_b128 v[152:155], v11 offset:12352
	ds_read_b128 v[156:159], v11 offset:12368
	ds_read_b128 v[160:163], v11 offset:12384
	ds_read_b128 v[164:167], v11 offset:12400
	ds_read_b128 v[180:183], v11 offset:16448
	ds_read_b128 v[184:187], v11 offset:16464
	ds_read_b128 v[188:191], v11 offset:16480
	ds_read_b128 v[192:195], v11 offset:16496
	s_waitcnt lgkmcnt(0)
	s_waitcnt vmcnt(15)
	v_fmac_f32_e32 v100, v16, v80
	v_fmac_f32_e32 v101, v17, v80
	v_fmac_f32_e32 v102, v18, v80
	v_fmac_f32_e32 v103, v19, v80
	v_fmac_f32_e32 v104, v16, v120
	v_fmac_f32_e32 v105, v17, v120
	v_fmac_f32_e32 v106, v18, v120
	v_fmac_f32_e32 v107, v19, v120
	v_fmac_f32_e32 v108, v16, v136
	v_fmac_f32_e32 v109, v17, v136
	v_fmac_f32_e32 v110, v18, v136
	v_fmac_f32_e32 v111, v19, v136
	v_fmac_f32_e32 v112, v16, v152
	v_fmac_f32_e32 v113, v17, v152
	v_fmac_f32_e32 v114, v18, v152
	v_fmac_f32_e32 v115, v19, v152
	v_fmac_f32_e32 v116, v16, v180
	v_fmac_f32_e32 v117, v17, v180
	v_fmac_f32_e32 v118, v18, v180
	v_fmac_f32_e32 v119, v19, v180
	s_waitcnt vmcnt(14)
	v_fmac_f32_e32 v100, v20, v81
	v_fmac_f32_e32 v101, v21, v81
	v_fmac_f32_e32 v102, v22, v81
	v_fmac_f32_e32 v103, v23, v81
	v_fmac_f32_e32 v104, v20, v121
	v_fmac_f32_e32 v105, v21, v121
	v_fmac_f32_e32 v106, v22, v121
	v_fmac_f32_e32 v107, v23, v121
	v_fmac_f32_e32 v108, v20, v137
	v_fmac_f32_e32 v109, v21, v137
	v_fmac_f32_e32 v110, v22, v137
	v_fmac_f32_e32 v111, v23, v137
	v_fmac_f32_e32 v112, v20, v153
	v_fmac_f32_e32 v113, v21, v153
	v_fmac_f32_e32 v114, v22, v153
	v_fmac_f32_e32 v115, v23, v153
	v_fmac_f32_e32 v116, v20, v181
	v_fmac_f32_e32 v117, v21, v181
	v_fmac_f32_e32 v118, v22, v181
	v_fmac_f32_e32 v119, v23, v181
	s_waitcnt vmcnt(13)
	v_fmac_f32_e32 v100, v24, v82
	v_fmac_f32_e32 v101, v25, v82
	v_fmac_f32_e32 v102, v26, v82
	v_fmac_f32_e32 v103, v27, v82
	v_fmac_f32_e32 v104, v24, v122
	v_fmac_f32_e32 v105, v25, v122
	v_fmac_f32_e32 v106, v26, v122
	v_fmac_f32_e32 v107, v27, v122
	v_fmac_f32_e32 v108, v24, v138
	v_fmac_f32_e32 v109, v25, v138
	v_fmac_f32_e32 v110, v26, v138
	v_fmac_f32_e32 v111, v27, v138
	v_fmac_f32_e32 v112, v24, v154
	v_fmac_f32_e32 v113, v25, v154
	v_fmac_f32_e32 v114, v26, v154
	v_fmac_f32_e32 v115, v27, v154
	v_fmac_f32_e32 v116, v24, v182
	v_fmac_f32_e32 v117, v25, v182
	v_fmac_f32_e32 v118, v26, v182
	v_fmac_f32_e32 v119, v27, v182
	s_waitcnt vmcnt(12)
	v_fmac_f32_e32 v100, v28, v83
	v_fmac_f32_e32 v101, v29, v83
	v_fmac_f32_e32 v102, v30, v83
	v_fmac_f32_e32 v103, v31, v83
	v_fmac_f32_e32 v104, v28, v123
	v_fmac_f32_e32 v105, v29, v123
	v_fmac_f32_e32 v106, v30, v123
	v_fmac_f32_e32 v107, v31, v123
	v_fmac_f32_e32 v108, v28, v139
	v_fmac_f32_e32 v109, v29, v139
	v_fmac_f32_e32 v110, v30, v139
	v_fmac_f32_e32 v111, v31, v139
	v_fmac_f32_e32 v112, v28, v155
	v_fmac_f32_e32 v113, v29, v155
	v_fmac_f32_e32 v114, v30, v155
	v_fmac_f32_e32 v115, v31, v155
	v_fmac_f32_e32 v116, v28, v183
	v_fmac_f32_e32 v117, v29, v183
	v_fmac_f32_e32 v118, v30, v183
	v_fmac_f32_e32 v119, v31, v183
	s_waitcnt vmcnt(11)
	v_fmac_f32_e32 v100, v32, v84
	v_fmac_f32_e32 v101, v33, v84
	v_fmac_f32_e32 v102, v34, v84
	v_fmac_f32_e32 v103, v35, v84
	v_fmac_f32_e32 v104, v32, v124
	v_fmac_f32_e32 v105, v33, v124
	v_fmac_f32_e32 v106, v34, v124
	v_fmac_f32_e32 v107, v35, v124
	v_fmac_f32_e32 v108, v32, v140
	v_fmac_f32_e32 v109, v33, v140
	v_fmac_f32_e32 v110, v34, v140
	v_fmac_f32_e32 v111, v35, v140
	v_fmac_f32_e32 v112, v32, v156
	v_fmac_f32_e32 v113, v33, v156
	v_fmac_f32_e32 v114, v34, v156
	v_fmac_f32_e32 v115, v35, v156
	v_fmac_f32_e32 v116, v32, v184
	v_fmac_f32_e32 v117, v33, v184
	v_fmac_f32_e32 v118, v34, v184
	v_fmac_f32_e32 v119, v35, v184
	s_waitcnt vmcnt(10)
	v_fmac_f32_e32 v100, v36, v85
	v_fmac_f32_e32 v101, v37, v85
	v_fmac_f32_e32 v102, v38, v85
	v_fmac_f32_e32 v103, v39, v85
	v_fmac_f32_e32 v104, v36, v125
	v_fmac_f32_e32 v105, v37, v125
	v_fmac_f32_e32 v106, v38, v125
	v_fmac_f32_e32 v107, v39, v125
	v_fmac_f32_e32 v108, v36, v141
	v_fmac_f32_e32 v109, v37, v141
	v_fmac_f32_e32 v110, v38, v141
	v_fmac_f32_e32 v111, v39, v141
	v_fmac_f32_e32 v112, v36, v157
	v_fmac_f32_e32 v113, v37, v157
	v_fmac_f32_e32 v114, v38, v157
	v_fmac_f32_e32 v115, v39, v157
	v_fmac_f32_e32 v116, v36, v185
	v_fmac_f32_e32 v117, v37, v185
	v_fmac_f32_e32 v118, v38, v185
	v_fmac_f32_e32 v119, v39, v185
	s_waitcnt vmcnt(9)
	v_fmac_f32_e32 v100, v40, v86
	v_fmac_f32_e32 v101, v41, v86
	v_fmac_f32_e32 v102, v42, v86
	v_fmac_f32_e32 v103, v43, v86
	v_fmac_f32_e32 v104, v40, v126
	v_fmac_f32_e32 v105, v41, v126
	v_fmac_f32_e32 v106, v42, v126
	v_fmac_f32_e32 v107, v43, v126
	v_fmac_f32_e32 v108, v40, v142
	v_fmac_f32_e32 v109, v41, v142
	v_fmac_f32_e32 v110, v42, v142
	v_fmac_f32_e32 v111, v43, v142
	v_fmac_f32_e32 v112, v40, v158
	v_fmac_f32_e32 v113, v41, v158
	v_fmac_f32_e32 v114, v42, v158
	v_fmac_f32_e32 v115, v43, v158
	v_fmac_f32_e32 v116, v40, v186
	v_fmac_f32_e32 v117, v41, v186
	v_fmac_f32_e32 v118, v42, v186
	v_fmac_f32_e32 v119, v43, v186
	s_waitcnt vmcnt(8)
	v_fmac_f32_e32 v100, v44, v87
	v_fmac_f32_e32 v101, v45, v87
	v_fmac_f32_e32 v102, v46, v87
	v_fmac_f32_e32 v103, v47, v87
	v_fmac_f32_e32 v104, v44, v127
	v_fmac_f32_e32 v105, v45, v127
	v_fmac_f32_e32 v106, v46, v127
	v_fmac_f32_e32 v107, v47, v127
	v_fmac_f32_e32 v108, v44, v143
	v_fmac_f32_e32 v109, v45, v143
	v_fmac_f32_e32 v110, v46, v143
	v_fmac_f32_e32 v111, v47, v143
	v_fmac_f32_e32 v112, v44, v159
	v_fmac_f32_e32 v113, v45, v159
	v_fmac_f32_e32 v114, v46, v159
	v_fmac_f32_e32 v115, v47, v159
	v_fmac_f32_e32 v116, v44, v187
	v_fmac_f32_e32 v117, v45, v187
	v_fmac_f32_e32 v118, v46, v187
	v_fmac_f32_e32 v119, v47, v187
	s_waitcnt vmcnt(7)
	v_fmac_f32_e32 v100, v48, v88
	v_fmac_f32_e32 v101, v49, v88
	v_fmac_f32_e32 v102, v50, v88
	v_fmac_f32_e32 v103, v51, v88
	v_fmac_f32_e32 v104, v48, v128
	v_fmac_f32_e32 v105, v49, v128
	v_fmac_f32_e32 v106, v50, v128
	v_fmac_f32_e32 v107, v51, v128
	v_fmac_f32_e32 v108, v48, v144
	v_fmac_f32_e32 v109, v49, v144
	v_fmac_f32_e32 v110, v50, v144
	v_fmac_f32_e32 v111, v51, v144
	v_fmac_f32_e32 v112, v48, v160
	v_fmac_f32_e32 v113, v49, v160
	v_fmac_f32_e32 v114, v50, v160
	v_fmac_f32_e32 v115, v51, v160
	v_fmac_f32_e32 v116, v48, v188
	v_fmac_f32_e32 v117, v49, v188
	v_fmac_f32_e32 v118, v50, v188
	v_fmac_f32_e32 v119, v51, v188
	s_waitcnt vmcnt(6)
	v_fmac_f32_e32 v100, v52, v89
	v_fmac_f32_e32 v101, v53, v89
	v_fmac_f32_e32 v102, v54, v89
	v_fmac_f32_e32 v103, v55, v89
	v_fmac_f32_e32 v104, v52, v129
	v_fmac_f32_e32 v105, v53, v129
	v_fmac_f32_e32 v106, v54, v129
	v_fmac_f32_e32 v107, v55, v129
	v_fmac_f32_e32 v108, v52, v145
	v_fmac_f32_e32 v109, v53, v145
	v_fmac_f32_e32 v110, v54, v145
	v_fmac_f32_e32 v111, v55, v145
	v_fmac_f32_e32 v112, v52, v161
	v_fmac_f32_e32 v113, v53, v161
	v_fmac_f32_e32 v114, v54, v161
	v_fmac_f32_e32 v115, v55, v161
	v_fmac_f32_e32 v116, v52, v189
	v_fmac_f32_e32 v117, v53, v189
	v_fmac_f32_e32 v118, v54, v189
	v_fmac_f32_e32 v119, v55, v189
	s_waitcnt vmcnt(5)
	v_fmac_f32_e32 v100, v56, v90
	v_fmac_f32_e32 v101, v57, v90
	v_fmac_f32_e32 v102, v58, v90
	v_fmac_f32_e32 v103, v59, v90
	v_fmac_f32_e32 v104, v56, v130
	v_fmac_f32_e32 v105, v57, v130
	v_fmac_f32_e32 v106, v58, v130
	v_fmac_f32_e32 v107, v59, v130
	v_fmac_f32_e32 v108, v56, v146
	v_fmac_f32_e32 v109, v57, v146
	v_fmac_f32_e32 v110, v58, v146
	v_fmac_f32_e32 v111, v59, v146
	v_fmac_f32_e32 v112, v56, v162
	v_fmac_f32_e32 v113, v57, v162
	v_fmac_f32_e32 v114, v58, v162
	v_fmac_f32_e32 v115, v59, v162
	v_fmac_f32_e32 v116, v56, v190
	v_fmac_f32_e32 v117, v57, v190
	v_fmac_f32_e32 v118, v58, v190
	v_fmac_f32_e32 v119, v59, v190
	s_waitcnt vmcnt(4)
	v_fmac_f32_e32 v100, v60, v91
	v_fmac_f32_e32 v101, v61, v91
	v_fmac_f32_e32 v102, v62, v91
	v_fmac_f32_e32 v103, v63, v91
	v_fmac_f32_e32 v104, v60, v131
	v_fmac_f32_e32 v105, v61, v131
	v_fmac_f32_e32 v106, v62, v131
	v_fmac_f32_e32 v107, v63, v131
	v_fmac_f32_e32 v108, v60, v147
	v_fmac_f32_e32 v109, v61, v147
	v_fmac_f32_e32 v110, v62, v147
	v_fmac_f32_e32 v111, v63, v147
	v_fmac_f32_e32 v112, v60, v163
	v_fmac_f32_e32 v113, v61, v163
	v_fmac_f32_e32 v114, v62, v163
	v_fmac_f32_e32 v115, v63, v163
	v_fmac_f32_e32 v116, v60, v191
	v_fmac_f32_e32 v117, v61, v191
	v_fmac_f32_e32 v118, v62, v191
	v_fmac_f32_e32 v119, v63, v191
	s_waitcnt vmcnt(3)
	v_fmac_f32_e32 v100, v64, v92
	v_fmac_f32_e32 v101, v65, v92
	v_fmac_f32_e32 v102, v66, v92
	v_fmac_f32_e32 v103, v67, v92
	v_fmac_f32_e32 v104, v64, v132
	v_fmac_f32_e32 v105, v65, v132
	v_fmac_f32_e32 v106, v66, v132
	v_fmac_f32_e32 v107, v67, v132
	v_fmac_f32_e32 v108, v64, v148
	v_fmac_f32_e32 v109, v65, v148
	v_fmac_f32_e32 v110, v66, v148
	v_fmac_f32_e32 v111, v67, v148
	v_fmac_f32_e32 v112, v64, v164
	v_fmac_f32_e32 v113, v65, v164
	v_fmac_f32_e32 v114, v66, v164
	v_fmac_f32_e32 v115, v67, v164
	v_fmac_f32_e32 v116, v64, v192
	v_fmac_f32_e32 v117, v65, v192
	v_fmac_f32_e32 v118, v66, v192
	v_fmac_f32_e32 v119, v67, v192
	s_waitcnt vmcnt(2)
	v_fmac_f32_e32 v100, v68, v93
	v_fmac_f32_e32 v101, v69, v93
	v_fmac_f32_e32 v102, v70, v93
	v_fmac_f32_e32 v103, v71, v93
	v_fmac_f32_e32 v104, v68, v133
	v_fmac_f32_e32 v105, v69, v133
	v_fmac_f32_e32 v106, v70, v133
	v_fmac_f32_e32 v107, v71, v133
	v_fmac_f32_e32 v108, v68, v149
	v_fmac_f32_e32 v109, v69, v149
	v_fmac_f32_e32 v110, v70, v149
	v_fmac_f32_e32 v111, v71, v149
	v_fmac_f32_e32 v112, v68, v165
	v_fmac_f32_e32 v113, v69, v165
	v_fmac_f32_e32 v114, v70, v165
	v_fmac_f32_e32 v115, v71, v165
	v_fmac_f32_e32 v116, v68, v193
	v_fmac_f32_e32 v117, v69, v193
	v_fmac_f32_e32 v118, v70, v193
	v_fmac_f32_e32 v119, v71, v193
	s_waitcnt vmcnt(1)
	v_fmac_f32_e32 v100, v72, v94
	v_fmac_f32_e32 v101, v73, v94
	v_fmac_f32_e32 v102, v74, v94
	v_fmac_f32_e32 v103, v75, v94
	v_fmac_f32_e32 v104, v72, v134
	v_fmac_f32_e32 v105, v73, v134
	v_fmac_f32_e32 v106, v74, v134
	v_fmac_f32_e32 v107, v75, v134
	v_fmac_f32_e32 v108, v72, v150
	v_fmac_f32_e32 v109, v73, v150
	v_fmac_f32_e32 v110, v74, v150
	v_fmac_f32_e32 v111, v75, v150
	v_fmac_f32_e32 v112, v72, v166
	v_fmac_f32_e32 v113, v73, v166
	v_fmac_f32_e32 v114, v74, v166
	v_fmac_f32_e32 v115, v75, v166
	v_fmac_f32_e32 v116, v72, v194
	v_fmac_f32_e32 v117, v73, v194
	v_fmac_f32_e32 v118, v74, v194
	v_fmac_f32_e32 v119, v75, v194
	s_waitcnt vmcnt(0)
	v_fmac_f32_e32 v100, v76, v95
	v_fmac_f32_e32 v101, v77, v95
	v_fmac_f32_e32 v102, v78, v95
	v_fmac_f32_e32 v103, v79, v95
	v_fmac_f32_e32 v104, v76, v135
	v_fmac_f32_e32 v105, v77, v135
	v_fmac_f32_e32 v106, v78, v135
	v_fmac_f32_e32 v107, v79, v135
	v_fmac_f32_e32 v108, v76, v151
	v_fmac_f32_e32 v109, v77, v151
	v_fmac_f32_e32 v110, v78, v151
	v_fmac_f32_e32 v111, v79, v151
	v_fmac_f32_e32 v112, v76, v167
	v_fmac_f32_e32 v113, v77, v167
	v_fmac_f32_e32 v114, v78, v167
	v_fmac_f32_e32 v115, v79, v167
	v_fmac_f32_e32 v116, v76, v195
	v_fmac_f32_e32 v117, v77, v195
	v_fmac_f32_e32 v118, v78, v195
	v_fmac_f32_e32 v119, v79, v195
	v_lshl_add_u32 v11, s16, 2, v13
	v_mul_u32_u24_e32 v11, 0x500, v11
	v_lshl_add_u32 v11, v12, 4, v11
	ds_write_b128 v11, v[100:103] offset:20480
	ds_write_b128 v11, v[104:107] offset:20736
	ds_write_b128 v11, v[108:111] offset:20992
	ds_write_b128 v11, v[112:115] offset:21248
	ds_write_b128 v11, v[116:119] offset:21504
	s_waitcnt lgkmcnt(0)
	s_barrier
	v_cmp_gt_u32_e32 vcc, 0x140, v1
	s_and_saveexec_b64 s[16:17], vcc
	s_cbranch_execz .Lgv_fin
	v_and_b32_e32 v12, 63, v1
	v_lshrrev_b32_e32 v13, 6, v1
	v_add_u32_e32 v14, s15, v12
	s_mul_i32 s20, s14, 0x1800
	v_add_u32_e32 v2, s20, v14
	v_lshlrev_b32_e32 v2, 2, v2
	global_load_dword v3, v2, s[34:35]
	v_lshlrev_b32_e32 v11, 8, v13
	v_lshl_add_u32 v11, v12, 2, v11
	ds_read_b32 v16, v11 offset:20480
	ds_read_b32 v17, v11 offset:21760
	ds_read_b32 v18, v11 offset:23040
	ds_read_b32 v19, v11 offset:24320
	ds_read_b32 v20, v11 offset:25600
	ds_read_b32 v21, v11 offset:26880
	ds_read_b32 v22, v11 offset:28160
	ds_read_b32 v23, v11 offset:29440
	ds_read_b32 v24, v11 offset:30720
	ds_read_b32 v25, v11 offset:32000
	ds_read_b32 v26, v11 offset:33280
	ds_read_b32 v27, v11 offset:34560
	ds_read_b32 v28, v11 offset:35840
	ds_read_b32 v29, v11 offset:37120
	ds_read_b32 v30, v11 offset:38400
	ds_read_b32 v31, v11 offset:39680
	ds_read_b32 v32, v11 offset:40960
	ds_read_b32 v33, v11 offset:42240
	ds_read_b32 v34, v11 offset:43520
	ds_read_b32 v35, v11 offset:44800
	ds_read_b32 v36, v11 offset:46080
	ds_read_b32 v37, v11 offset:47360
	ds_read_b32 v38, v11 offset:48640
	ds_read_b32 v39, v11 offset:49920
	ds_read_b32 v40, v11 offset:51200
	ds_read_b32 v41, v11 offset:52480
	ds_read_b32 v42, v11 offset:53760
	ds_read_b32 v43, v11 offset:55040
	ds_read_b32 v44, v11 offset:56320
	ds_read_b32 v45, v11 offset:57600
	ds_read_b32 v46, v11 offset:58880
	ds_read_b32 v47, v11 offset:60160
	s_waitcnt vmcnt(0)
	s_waitcnt lgkmcnt(15)
	v_add_f32_e32 v3, v3, v16
	s_waitcnt lgkmcnt(15)
	v_add_f32_e32 v3, v3, v17
	s_waitcnt lgkmcnt(15)
	v_add_f32_e32 v3, v3, v18
	s_waitcnt lgkmcnt(15)
	v_add_f32_e32 v3, v3, v19
	s_waitcnt lgkmcnt(15)
	v_add_f32_e32 v3, v3, v20
	s_waitcnt lgkmcnt(15)
	v_add_f32_e32 v3, v3, v21
	s_waitcnt lgkmcnt(15)
	v_add_f32_e32 v3, v3, v22
	s_waitcnt lgkmcnt(15)
	v_add_f32_e32 v3, v3, v23
	s_waitcnt lgkmcnt(15)
	v_add_f32_e32 v3, v3, v24
	s_waitcnt lgkmcnt(15)
	v_add_f32_e32 v3, v3, v25
	s_waitcnt lgkmcnt(15)
	v_add_f32_e32 v3, v3, v26
	s_waitcnt lgkmcnt(15)
	v_add_f32_e32 v3, v3, v27
	s_waitcnt lgkmcnt(15)
	v_add_f32_e32 v3, v3, v28
	s_waitcnt lgkmcnt(15)
	v_add_f32_e32 v3, v3, v29
	s_waitcnt lgkmcnt(15)
	v_add_f32_e32 v3, v3, v30
	s_waitcnt lgkmcnt(15)
	v_add_f32_e32 v3, v3, v31
	s_waitcnt lgkmcnt(15)
	v_add_f32_e32 v3, v3, v32
	s_waitcnt lgkmcnt(14)
	v_add_f32_e32 v3, v3, v33
	s_waitcnt lgkmcnt(13)
	v_add_f32_e32 v3, v3, v34
	s_waitcnt lgkmcnt(12)
	v_add_f32_e32 v3, v3, v35
	s_waitcnt lgkmcnt(11)
	v_add_f32_e32 v3, v3, v36
	s_waitcnt lgkmcnt(10)
	v_add_f32_e32 v3, v3, v37
	s_waitcnt lgkmcnt(9)
	v_add_f32_e32 v3, v3, v38
	s_waitcnt lgkmcnt(8)
	v_add_f32_e32 v3, v3, v39
	s_waitcnt lgkmcnt(7)
	v_add_f32_e32 v3, v3, v40
	s_waitcnt lgkmcnt(6)
	v_add_f32_e32 v3, v3, v41
	s_waitcnt lgkmcnt(5)
	v_add_f32_e32 v3, v3, v42
	s_waitcnt lgkmcnt(4)
	v_add_f32_e32 v3, v3, v43
	s_waitcnt lgkmcnt(3)
	v_add_f32_e32 v3, v3, v44
	s_waitcnt lgkmcnt(2)
	v_add_f32_e32 v3, v3, v45
	s_waitcnt lgkmcnt(1)
	v_add_f32_e32 v3, v3, v46
	s_waitcnt lgkmcnt(0)
	v_add_f32_e32 v3, v3, v47
	s_lshr_b32 s20, s15, 10
	v_and_b32_e32 v14, 0x3ff, v14
	s_mul_i32 s21, s14, 5
	v_add_u32_e32 v4, s21, v13
	v_mul_u32_u24_e32 v4, 0x1800, v4
	v_add_u32_e32 v4, v4, v14
	v_lshlrev_b32_e32 v4, 2, v4
	s_add_u32 s26, s10, 0x780000
	s_addc_u32 s27, s11, 0
	s_cmp_lg_u32 s20, 0
	s_cbranch_scc1 .Lgv_j0
	v_add_u32_e32 v4, 0x1000, v4
	global_store_dword v4, v3, s[26:27]
	s_branch .Lgv_fin
.Lgv_j0:
	s_cmp_lg_u32 s20, 1
	s_cbranch_scc1 .Lgv_j1
	s_mul_i32 s21, s14, 2
	s_lshl_b32 s21, s21, 12
	v_lshl_add_u32 v5, v14, 2, s21
	global_load_dword v6, v5, s[36:37]
	v_add_f32_e32 v3, 1.0, v3
	s_waitcnt vmcnt(0)
	v_mul_f32_e32 v3, v6, v3
	global_store_dword v4, v3, s[26:27]
	s_branch .Lgv_fin
.Lgv_j1:
	s_cmp_lg_u32 s20, 2
	s_cbranch_scc1 .Lgv_j2
	v_add_u32_e32 v4, 0x2000, v4
	global_store_dword v4, v3, s[26:27]
	s_branch .Lgv_fin
.Lgv_j2:
	s_cmp_lg_u32 s20, 3
	s_cbranch_scc1 .Lgv_j3
	v_add_u32_e32 v4, 0x4000, v4
	global_store_dword v4, v3, s[26:27]
	s_branch .Lgv_fin
.Lgv_j3:
	s_cmp_lg_u32 s20, 4
	s_cbranch_scc1 .Lgv_j4
	s_mul_i32 s21, s14, 2
	s_add_i32 s21, s21, 1
	s_lshl_b32 s21, s21, 12
	v_lshl_add_u32 v5, v14, 2, s21
	global_load_dword v6, v5, s[36:37]
	v_add_f32_e32 v3, 1.0, v3
	s_waitcnt vmcnt(0)
	v_mul_f32_e32 v3, v6, v3
	v_add_u32_e32 v4, 0x3000, v4
	global_store_dword v4, v3, s[26:27]
	s_branch .Lgv_fin
.Lgv_j4:
	s_cmp_lg_u32 s20, 5
	s_cbranch_scc1 .Lgv_j5
	v_add_u32_e32 v4, 0x5000, v4
	global_store_dword v4, v3, s[26:27]
	s_branch .Lgv_fin
.Lgv_j5:
.Lgv_fin:
	s_or_b64 exec, exec, s[16:17]
.Lgv_end:
.LBB0_17:
	s_load_dwordx2 s[4:5], s[0:1], 0xe8
	s_getreg_b32 s3, hwreg(HW_REG_XCC_ID, 0, 4)
	s_and_saveexec_b64 s[6:7], s[38:39]
	s_cbranch_execz .Lgs_done
	s_load_dwordx2 s[8:9], s[88:89], 0x58
	v_mov_b32_e32 v0, 0
	s_mov_b32 s10, 0
	s_waitcnt lgkmcnt(0)

.LBB0_30:
	s_or_b64 exec, exec, s[6:7]
	s_mov_b64 s[4:5], s[0:1]
	v_mov_b32_e32 v0, v170
	s_cmpk_gt_i32 s2, 0xdf
	s_cbranch_scc1 .LBB0_71
	s_load_dwordx2 s[6:7], s[4:5], 0xe8
	v_add_u32_e32 v4, 0x200, v0
	v_ashrrev_i32_e32 v11, 6, v4
	v_add_u32_e32 v4, 0x400, v0
	v_ashrrev_i32_e32 v12, 6, v4
	v_add_u32_e32 v4, 0x600, v0
	v_ashrrev_i32_e32 v13, 6, v4
	v_add_u32_e32 v4, 0x800, v0
	s_waitcnt lgkmcnt(0)
	s_add_u32 s8, s6, 0x780000
	v_ashrrev_i32_e32 v14, 6, v4
	v_add_u32_e32 v4, 0xa00, v0
	s_addc_u32 s9, s7, 0
	v_ashrrev_i32_e32 v15, 6, v4
	v_add_u32_e32 v4, 0xc00, v0
	s_add_u32 s3, s6, 0xe3c000
	v_ashrrev_i32_e32 v16, 6, v4
	v_add_u32_e32 v4, 0xe00, v0
	s_addc_u32 s30, s7, 0
	v_ashrrev_i32_e32 v17, 6, v4
	v_bfe_u32 v4, v0, 4, 2
	v_lshlrev_b32_e32 v5, 4, v0
	v_lshlrev_b32_e32 v3, 3, v0
	s_add_u32 s10, s6, 0xdbc000
	v_mul_u32_u24_e32 v4, 0x4100, v4
	v_and_b32_e32 v5, 0xf0, v5
	s_addc_u32 s11, s7, 0
	v_add3_u32 v5, 0, v4, v5
	v_and_b32_e32 v4, 56, v3
	s_add_u32 s12, s6, 0xbbc000
	v_ashrrev_i32_e32 v18, 3, v0
	v_mul_u32_u24_e32 v3, 0x41, v4
	v_ashrrev_i32_e32 v10, 6, v0
	v_lshlrev_b32_e32 v1, 2, v0
	s_addc_u32 s13, s7, 0
	s_movk_i32 s16, 0x104
	v_lshlrev_b32_e32 v20, 2, v18
	v_lshlrev_b32_e32 v3, 2, v3
	v_and_b32_e32 v2, 0xfc, v1
	s_add_u32 s14, s6, 0x7bc000
	v_mul_lo_u32 v6, v10, s16
	v_mul_lo_u32 v7, v11, s16
	v_mul_lo_u32 v8, v12, s16
	v_mul_lo_u32 v9, v13, s16
	v_mul_lo_u32 v26, v14, s16
	v_mul_lo_u32 v27, v15, s16
	v_mul_lo_u32 v28, v16, s16
	v_mul_lo_u32 v29, v17, s16
	v_add3_u32 v19, 0, v20, v3
	v_add3_u32 v20, 0, v3, v20
	s_addc_u32 s15, s7, 0
	v_mov_b32_e32 v1, 0
	s_mov_b32 s17, 0
	v_lshl_add_u32 v21, s2, 9, v0
	s_lshl_b32 s31, s42, 9
	v_lshlrev_b32_e32 v2, 2, v2
	v_add_u32_e32 v22, v5, v6
	v_add_u32_e32 v23, v5, v7
	v_add_u32_e32 v24, v5, v8
	v_add_u32_e32 v25, v5, v9
	v_add_u32_e32 v26, v5, v26
	v_add_u32_e32 v27, v5, v27
	v_add_u32_e32 v28, v5, v28
	v_add_u32_e32 v29, v5, v29
	v_lshlrev_b32_e32 v4, 1, v4
	s_mov_b32 s34, 0x88888889
	s_movk_i32 s35, 0x8800
	s_mov_b32 s36, 0x2aaaaaab
	s_movk_i32 s37, 0x6000
	s_movk_i32 s40, 0x3ff
	v_add_u32_e32 v30, 0x400, v19
	v_add_u32_e32 v31, 0x400, v20
	v_add_u32_e32 v32, 0x4000, v19
	v_add_u32_e32 v33, 0x4200, v20
	v_add_u32_e32 v34, 0x4400, v19
	v_add_u32_e32 v35, 0x4600, v20
	v_add_u32_e32 v36, 0x8200, v19
	v_add_u32_e32 v37, 0x8200, v20
	v_add_u32_e32 v38, 0x8600, v19
	v_add_u32_e32 v39, 0x8600, v20
	v_add_u32_e32 v40, 0xc200, v19
	v_add_u32_e32 v41, 0xc400, v20
	v_add_u32_e32 v42, 0xc600, v19
	v_add_u32_e32 v43, 0xc800, v20
	s_add_i32 s41, s2, 0x78
	s_branch .LBB0_34

.LBB0_123:
	s_or_b64 exec, exec, s[4:5]
	s_mov_b64 s[4:5], s[0:1]
	v_mov_b32_e32 v2, v170
	s_waitcnt lgkmcnt(0)
	s_barrier
	v_mov_b32_e32 v4, 0x22000
	ds_read_b32 v5, v4
	ds_read_b32 v6, v4 offset:4
	s_mov_b32 s98, 1
	s_waitcnt lgkmcnt(0)
	v_readfirstlane_b32 s99, v5
	v_readfirstlane_b32 s100, v6
	s_cmp_lg_u32 s2, 0
	s_cbranch_scc1 .Lgs_noreset
	s_and_saveexec_b64 s[6:7], s[38:39]
	s_load_dwordx2 s[8:9], s[88:89], 0x58
	v_mov_b32_e32 v0, 0
	v_mov_b32_e32 v1, -1
	s_waitcnt lgkmcnt(0)
	global_atomic_add v0, v1, s[8:9] offset:32
	s_or_b64 exec, exec, s[6:7]
.Lgs_noreset:
	s_lshl_b32 s46, s2, 3
	v_ashrrev_i32_e32 v0, 6, v2
	v_add_u32_e32 v3, s46, v0
	s_movk_i32 s3, 0x3000
	s_lshl_b32 s44, s42, 3
	v_cmp_gt_i32_e32 vcc, s3, v3
	v_mbcnt_lo_u32_b32 v135, -1, 0
	s_and_saveexec_b64 s[10:11], vcc
	s_cbranch_execz .LBB0_134
	v_lshlrev_b32_e32 v1, 2, v2
	v_and_b32_e32 v4, 0xfc, v1
	v_mbcnt_hi_u32_b32 v1, -1, v135
	v_and_b32_e32 v6, 64, v1
	v_xor_b32_e32 v5, 32, v1
	v_add_u32_e32 v6, 64, v6
	v_cmp_lt_i32_e32 vcc, v5, v6
	s_load_dwordx2 s[6:7], s[4:5], 0xe8
	s_load_dwordx4 s[12:15], s[4:5], 0x0
	v_cndmask_b32_e32 v5, v1, v5, vcc
	v_lshlrev_b32_e32 v66, 2, v5
	v_xor_b32_e32 v5, 16, v1
	v_cmp_lt_i32_e32 vcc, v5, v6
	s_waitcnt lgkmcnt(0)
	s_add_u32 s18, s6, 0x780000
	s_addc_u32 s19, s7, 0
	v_cndmask_b32_e32 v5, v1, v5, vcc
	v_lshlrev_b32_e32 v67, 2, v5
	v_xor_b32_e32 v5, 8, v1
	v_cmp_lt_i32_e32 vcc, v5, v6
	s_ashr_i32 s47, s46, 31
	v_add_u32_e32 v56, s44, v3
	v_cndmask_b32_e32 v5, v1, v5, vcc
	v_lshlrev_b32_e32 v68, 2, v5
	v_xor_b32_e32 v5, 4, v1
	v_cmp_lt_i32_e32 vcc, v5, v6
	v_ashrrev_i32_e32 v57, 31, v56
	v_mov_b32_e32 v49, 0
	v_cndmask_b32_e32 v5, v1, v5, vcc
	v_lshlrev_b32_e32 v69, 2, v5
	v_xor_b32_e32 v5, 2, v1
	v_cmp_lt_i32_e32 vcc, v5, v6
	v_lshlrev_b32_e32 v48, 1, v4
	s_mov_b32 s17, 0
	v_cndmask_b32_e32 v5, v1, v5, vcc
	v_lshlrev_b32_e32 v70, 2, v5
	v_xor_b32_e32 v5, 1, v1
	v_cmp_lt_i32_e32 vcc, v5, v6
	v_lshl_add_u64 v[6:7], s[6:7], 0, v[48:49]
	s_mov_b64 s[4:5], 0x2ebc000
	v_cndmask_b32_e32 v1, v1, v5, vcc
	v_lshlrev_b32_e32 v71, 2, v1
	v_ashrrev_i32_e32 v1, 31, v0
	v_lshl_add_u64 v[52:53], v[0:1], 0, s[46:47]
	v_and_b32_e32 v0, 63, v2
	v_lshlrev_b32_e32 v54, 3, v0
	v_lshlrev_b64 v[0:1], 11, v[56:57]
	s_mul_i32 s20, s42, 24
	v_lshl_add_u64 v[58:59], s[6:7], 0, v[0:1]
	v_lshlrev_b64 v[0:1], 11, v[52:53]
	v_lshl_add_u64 v[50:51], v[6:7], 0, s[4:5]
	s_mov_b32 s45, s17
	s_ashr_i32 s21, s20, 31
	v_lshl_add_u64 v[0:1], s[6:7], 0, v[0:1]
	s_mov_b64 s[4:5], 0x2ebc400
	s_lshl_b32 s16, s42, 4
	v_mov_b32_e32 v55, v49
	s_lshl_b64 s[22:23], s[20:21], 11
	v_lshl_add_u64 v[60:61], v[0:1], 0, s[4:5]
	s_mov_b64 s[24:25], 0
	s_movk_i32 s40, 0x1000
	v_mov_b32_e32 v72, s15
	v_mov_b32_e32 v73, s13
	v_mov_b32_e32 v74, s14
	v_mov_b32_e32 v75, s12
	v_lshlrev_b32_e32 v48, 2, v4
	v_mov_b32_e32 v76, 0x358637bd
	s_mov_b32 s41, 0x800000
	s_mov_b64 s[26:27], 0x1000
	s_movk_i32 s47, 0xfff
	s_mov_b32 s52, 0x2ebc000
	s_movk_i32 s53, 0x2fff
	s_mov_b64 s[28:29], 0
	s_mov_b64 s[30:31], s[44:45]
	s_mov_b64 s[34:35], 0
	s_branch .LBB0_126
